# A, B and D attention loops: waves 4-7 run P.V right after the tile barrier and issue their K/V LDS-DMA pieces after P.V
# baseline (speedup 1.0000x reference)
.LBB0_388:
	s_add_i32 s0, s81, s13
	s_waitcnt vmcnt(4) lgkmcnt(0)
	s_barrier
	s_branch .Lmy_r2a_0

.Lmy_fta_0:
	s_cmpk_gt_u32 s18, 0xfc
	s_mov_b64 s[6:7], -1
	s_cbranch_scc1 .LBB0_423
	s_andn2_b64 vcc, exec, s[6:7]
	s_cbranch_vccnz .LBB0_394

.LBB0_401:
	s_add_i32 s6, s81, s20
	s_waitcnt vmcnt(4) lgkmcnt(0)
	s_barrier
	s_branch .Lmy_r2a_1

.Lmy_fta_1:
	s_cmpk_gt_u32 s18, 0xfb
	s_mov_b64 s[6:7], -1
	s_cbranch_scc1 .LBB0_429
	s_andn2_b64 vcc, exec, s[6:7]
	s_cbranch_vccnz .LBB0_406

; #define SBAR() __builtin_amdgcn_sched_barrier(0)
; template <int D0> __device__ __forceinline__ void pv_one(f32x16& od, int vb, bf16x8 pa0, bf16x8 pa1, bf16x8 pa2, bf16x8 pa3) {
;     const s16x4 l0 = tr_read<v_rd_off(D0, 0, 0)>(vb), h0 = tr_read<v_rd_off(D0, 0, 1)>(vb), l1 = tr_read<v_rd_off(D0, 1, 0)>(vb), h1 = tr_read<v_rd_off(D0, 1, 1)>(vb);
;     const s16x4 l2 = tr_read<v_rd_off(D0, 2, 0)>(vb), h2 = tr_read<v_rd_off(D0, 2, 1)>(vb), l3 = tr_read<v_rd_off(D0, 3, 0)>(vb), h3 = tr_read<v_rd_off(D0, 3, 1)>(vb);
;     asm volatile("s_waitcnt lgkmcnt(0)" ::: "memory"); SBAR();
;     ...
;     od = __builtin_amdgcn_mfma_f32_32x32x16_bf16(pa0, PK(l0, h0), od, 0, 0, 0);
;     od = __builtin_amdgcn_mfma_f32_32x32x16_bf16(pa1, PK(l1, h1), od, 0, 0, 0);
;     od = __builtin_amdgcn_mfma_f32_32x32x16_bf16(pa2, PK(l2, h2), od, 0, 0, 0);
;     od = __builtin_amdgcn_mfma_f32_32x32x16_bf16(pa3, PK(l3, h3), od, 0, 0, 0);
;     ...
; }
; template <bool RSM> __device__ __forceinline__ void pv_d0(f32x16* o, f32x16& lacc, int vb, bf16x8 pa0, bf16x8 pa1, bf16x8 pa2, bf16x8 pa3) {
;     if (RSM) {
;         const bf16x8 ones = {0x3F80, 0x3F80, 0x3F80, 0x3F80, 0x3F80, 0x3F80, 0x3F80, 0x3F80};
;         lacc = __builtin_amdgcn_mfma_f32_32x32x16_bf16(pa0, ones, lacc, 0, 0, 0);
;         lacc = __builtin_amdgcn_mfma_f32_32x32x16_bf16(pa1, ones, lacc, 0, 0, 0);
;         lacc = __builtin_amdgcn_mfma_f32_32x32x16_bf16(pa2, ones, lacc, 0, 0, 0);
;         lacc = __builtin_amdgcn_mfma_f32_32x32x16_bf16(pa3, ones, lacc, 0, 0, 0); }
;     pv_one<0>(o[0], vb, pa0, pa1, pa2, pa3); pv_one<1>(o[1], vb, pa0, pa1, pa2, pa3); pv_one<2>(o[2], vb, pa0, pa1, pa2, pa3); pv_one<3>(o[3], vb, pa0, pa1, pa2, pa3);
.Lmy_r2a_0:
	s_lshl_b32 s19, s16, 14
	v_add_u32_e32 v14, s19, v196
	ds_read_b64_tr_b16 v[100:101], v14 offset:0
	ds_read_b64_tr_b16 v[102:103], v14 offset:0x800
	ds_read_b64_tr_b16 v[104:105], v14 offset:0x1000
	ds_read_b64_tr_b16 v[106:107], v14 offset:0x1800
	ds_read_b64_tr_b16 v[108:109], v14 offset:0x2000
	ds_read_b64_tr_b16 v[110:111], v14 offset:0x2800
	ds_read_b64_tr_b16 v[176:177], v14 offset:0x3000
	ds_read_b64_tr_b16 v[178:179], v14 offset:0x3800
	s_waitcnt lgkmcnt(0)
	s_nop 0
	v_mfma_f32_32x32x16_bf16 v[64:79], v[2:5], v[100:103], v[64:79]
	ds_read_b64_tr_b16 v[100:101], v14 offset:0x200
	ds_read_b64_tr_b16 v[102:103], v14 offset:0xa00
	v_mfma_f32_32x32x16_bf16 v[64:79], v[6:9], v[104:107], v[64:79]
	ds_read_b64_tr_b16 v[104:105], v14 offset:0x1200
	ds_read_b64_tr_b16 v[106:107], v14 offset:0x1a00
	v_mfma_f32_32x32x16_bf16 v[64:79], v[10:13], v[108:111], v[64:79]
	ds_read_b64_tr_b16 v[108:109], v14 offset:0x2200
	ds_read_b64_tr_b16 v[110:111], v14 offset:0x2a00
	v_mfma_f32_32x32x16_bf16 v[64:79], v[96:99], v[176:179], v[64:79]
	ds_read_b64_tr_b16 v[176:177], v14 offset:0x3200
	ds_read_b64_tr_b16 v[178:179], v14 offset:0x3a00
	s_waitcnt lgkmcnt(0)
	v_mfma_f32_32x32x16_bf16 v[48:63], v[2:5], v[100:103], v[48:63]
	ds_read_b64_tr_b16 v[100:101], v14 offset:0x400
	ds_read_b64_tr_b16 v[102:103], v14 offset:0xc00
	v_mfma_f32_32x32x16_bf16 v[48:63], v[6:9], v[104:107], v[48:63]
	ds_read_b64_tr_b16 v[104:105], v14 offset:0x1400
	ds_read_b64_tr_b16 v[106:107], v14 offset:0x1c00
	v_mfma_f32_32x32x16_bf16 v[48:63], v[10:13], v[108:111], v[48:63]
	ds_read_b64_tr_b16 v[108:109], v14 offset:0x2400
	ds_read_b64_tr_b16 v[110:111], v14 offset:0x2c00
	v_mfma_f32_32x32x16_bf16 v[48:63], v[96:99], v[176:179], v[48:63]
	ds_read_b64_tr_b16 v[176:177], v14 offset:0x3400
	ds_read_b64_tr_b16 v[178:179], v14 offset:0x3c00
	s_waitcnt lgkmcnt(0)
	v_mfma_f32_32x32x16_bf16 v[32:47], v[2:5], v[100:103], v[32:47]
	ds_read_b64_tr_b16 v[100:101], v14 offset:0x600
	ds_read_b64_tr_b16 v[102:103], v14 offset:0xe00
	v_mfma_f32_32x32x16_bf16 v[32:47], v[6:9], v[104:107], v[32:47]
	ds_read_b64_tr_b16 v[104:105], v14 offset:0x1600
	ds_read_b64_tr_b16 v[106:107], v14 offset:0x1e00
	v_mfma_f32_32x32x16_bf16 v[32:47], v[10:13], v[108:111], v[32:47]
	ds_read_b64_tr_b16 v[108:109], v14 offset:0x2600
	ds_read_b64_tr_b16 v[110:111], v14 offset:0x2e00
	v_mfma_f32_32x32x16_bf16 v[32:47], v[96:99], v[176:179], v[32:47]
	ds_read_b64_tr_b16 v[176:177], v14 offset:0x3600
	ds_read_b64_tr_b16 v[178:179], v14 offset:0x3e00
	s_waitcnt lgkmcnt(0)
	v_mfma_f32_32x32x16_bf16 v[16:31], v[2:5], v[100:103], v[16:31]
	v_cndmask_b32_e64 v2, 0, 1, s[54:55]
	v_cmp_ne_u32_e64 s[0:1], 1, v2
	s_andn2_b64 vcc, exec, s[54:55]
	v_mfma_f32_32x32x16_bf16 v[16:31], v[6:9], v[104:107], v[16:31]
	v_mfma_f32_32x32x16_bf16 v[16:31], v[10:13], v[108:111], v[16:31]
	v_mfma_f32_32x32x16_bf16 v[16:31], v[96:99], v[176:179], v[16:31]
	s_add_i32 s6, s81, s13
	s_mov_b32 m0, s6
	v_lshl_add_u64 v[14:15], v[186:187], 0, s[74:75]
	global_load_lds_dwordx4 v[184:185], off
	s_add_i32 m0, s6, 0x2000
	s_lshl_b32 s6, s16, 14
	s_addk_i32 s6, 0xc000
	s_cmp_gt_i32 s16, 0
	s_cselect_b32 s6, s6, 0xc000
	s_add_i32 s6, s63, s6
	global_load_lds_dwordx4 v[188:189], off
	s_mov_b32 m0, s6
	v_lshl_add_u64 v[184:185], v[184:185], 0, s[74:75]
	global_load_lds_dwordx4 v[186:187], off
	s_add_i32 m0, s6, 0x2000
	v_lshl_add_u64 v[188:189], v[188:189], 0, s[74:75]
	global_load_lds_dwordx4 v[190:191], off
	v_lshl_add_u64 v[100:101], v[190:191], 0, s[74:75]
	v_mov_b64_e32 v[190:191], v[100:101]
	v_mov_b64_e32 v[186:187], v[14:15]
	s_cbranch_vccnz .LBB0_395
	s_branch .Lmy_fta_0
; #define SBAR() __builtin_amdgcn_sched_barrier(0)
; template <int D0> __device__ __forceinline__ void pv_one(f32x16& od, int vb, bf16x8 pa0, bf16x8 pa1, bf16x8 pa2, bf16x8 pa3) {
;     const s16x4 l0 = tr_read<v_rd_off(D0, 0, 0)>(vb), h0 = tr_read<v_rd_off(D0, 0, 1)>(vb), l1 = tr_read<v_rd_off(D0, 1, 0)>(vb), h1 = tr_read<v_rd_off(D0, 1, 1)>(vb);
;     const s16x4 l2 = tr_read<v_rd_off(D0, 2, 0)>(vb), h2 = tr_read<v_rd_off(D0, 2, 1)>(vb), l3 = tr_read<v_rd_off(D0, 3, 0)>(vb), h3 = tr_read<v_rd_off(D0, 3, 1)>(vb);
;     asm volatile("s_waitcnt lgkmcnt(0)" ::: "memory"); SBAR();
;     ...
;     od = __builtin_amdgcn_mfma_f32_32x32x16_bf16(pa0, PK(l0, h0), od, 0, 0, 0);
;     od = __builtin_amdgcn_mfma_f32_32x32x16_bf16(pa1, PK(l1, h1), od, 0, 0, 0);
;     od = __builtin_amdgcn_mfma_f32_32x32x16_bf16(pa2, PK(l2, h2), od, 0, 0, 0);
;     od = __builtin_amdgcn_mfma_f32_32x32x16_bf16(pa3, PK(l3, h3), od, 0, 0, 0);
;     ...
; }
; template <bool RSM> __device__ __forceinline__ void pv_d0(f32x16* o, f32x16& lacc, int vb, bf16x8 pa0, bf16x8 pa1, bf16x8 pa2, bf16x8 pa3) {
;     if (RSM) {
;         const bf16x8 ones = {0x3F80, 0x3F80, 0x3F80, 0x3F80, 0x3F80, 0x3F80, 0x3F80, 0x3F80};
;         lacc = __builtin_amdgcn_mfma_f32_32x32x16_bf16(pa0, ones, lacc, 0, 0, 0);
;         lacc = __builtin_amdgcn_mfma_f32_32x32x16_bf16(pa1, ones, lacc, 0, 0, 0);
;         lacc = __builtin_amdgcn_mfma_f32_32x32x16_bf16(pa2, ones, lacc, 0, 0, 0);
;         lacc = __builtin_amdgcn_mfma_f32_32x32x16_bf16(pa3, ones, lacc, 0, 0, 0); }
;     pv_one<0>(o[0], vb, pa0, pa1, pa2, pa3); pv_one<1>(o[1], vb, pa0, pa1, pa2, pa3); pv_one<2>(o[2], vb, pa0, pa1, pa2, pa3); pv_one<3>(o[3], vb, pa0, pa1, pa2, pa3);
.Lmy_r2a_1:
	s_lshl_b32 s12, s13, 14
	v_add_u32_e32 v117, s12, v196
	ds_read_b64_tr_b16 v[118:119], v117 offset:0
	ds_read_b64_tr_b16 v[120:121], v117 offset:0x800
	ds_read_b64_tr_b16 v[122:123], v117 offset:0x1000
	ds_read_b64_tr_b16 v[124:125], v117 offset:0x1800
	ds_read_b64_tr_b16 v[176:177], v117 offset:0x2000
	ds_read_b64_tr_b16 v[178:179], v117 offset:0x2800
	ds_read_b64_tr_b16 v[180:181], v117 offset:0x3000
	ds_read_b64_tr_b16 v[182:183], v117 offset:0x3800
	s_waitcnt lgkmcnt(0)
	s_nop 0
	v_mfma_f32_32x32x16_bf16 v[64:79], v[2:5], v[118:121], v[64:79]
	ds_read_b64_tr_b16 v[118:119], v117 offset:0x200
	ds_read_b64_tr_b16 v[120:121], v117 offset:0xa00
	v_mfma_f32_32x32x16_bf16 v[64:79], v[6:9], v[122:125], v[64:79]
	ds_read_b64_tr_b16 v[122:123], v117 offset:0x1200
	ds_read_b64_tr_b16 v[124:125], v117 offset:0x1a00
	v_mfma_f32_32x32x16_bf16 v[64:79], v[10:13], v[176:179], v[64:79]
	ds_read_b64_tr_b16 v[176:177], v117 offset:0x2200
	ds_read_b64_tr_b16 v[178:179], v117 offset:0x2a00
	v_mfma_f32_32x32x16_bf16 v[64:79], v[112:115], v[180:183], v[64:79]
	ds_read_b64_tr_b16 v[180:181], v117 offset:0x3200
	ds_read_b64_tr_b16 v[182:183], v117 offset:0x3a00
	s_waitcnt lgkmcnt(0)
	v_mfma_f32_32x32x16_bf16 v[48:63], v[2:5], v[118:121], v[48:63]
	ds_read_b64_tr_b16 v[118:119], v117 offset:0x400
	ds_read_b64_tr_b16 v[120:121], v117 offset:0xc00
	v_mfma_f32_32x32x16_bf16 v[48:63], v[6:9], v[122:125], v[48:63]
	ds_read_b64_tr_b16 v[122:123], v117 offset:0x1400
	ds_read_b64_tr_b16 v[124:125], v117 offset:0x1c00
	v_mfma_f32_32x32x16_bf16 v[48:63], v[10:13], v[176:179], v[48:63]
	ds_read_b64_tr_b16 v[176:177], v117 offset:0x2400
	ds_read_b64_tr_b16 v[178:179], v117 offset:0x2c00
	v_mfma_f32_32x32x16_bf16 v[48:63], v[112:115], v[180:183], v[48:63]
	ds_read_b64_tr_b16 v[180:181], v117 offset:0x3400
	ds_read_b64_tr_b16 v[182:183], v117 offset:0x3c00
	s_waitcnt lgkmcnt(0)
	v_mfma_f32_32x32x16_bf16 v[32:47], v[2:5], v[118:121], v[32:47]
	ds_read_b64_tr_b16 v[118:119], v117 offset:0x600
	ds_read_b64_tr_b16 v[120:121], v117 offset:0xe00
	v_mfma_f32_32x32x16_bf16 v[32:47], v[6:9], v[122:125], v[32:47]
	ds_read_b64_tr_b16 v[122:123], v117 offset:0x1600
	ds_read_b64_tr_b16 v[124:125], v117 offset:0x1e00
	v_mfma_f32_32x32x16_bf16 v[32:47], v[10:13], v[176:179], v[32:47]
	ds_read_b64_tr_b16 v[176:177], v117 offset:0x2600
	ds_read_b64_tr_b16 v[178:179], v117 offset:0x2e00
	v_mfma_f32_32x32x16_bf16 v[32:47], v[112:115], v[180:183], v[32:47]
	ds_read_b64_tr_b16 v[180:181], v117 offset:0x3600
	ds_read_b64_tr_b16 v[182:183], v117 offset:0x3e00
	s_waitcnt lgkmcnt(0)
	v_mfma_f32_32x32x16_bf16 v[16:31], v[2:5], v[118:121], v[16:31]
	s_and_b64 vcc, exec, s[0:1]
	v_mfma_f32_32x32x16_bf16 v[16:31], v[6:9], v[122:125], v[16:31]
	v_mfma_f32_32x32x16_bf16 v[16:31], v[10:13], v[176:179], v[16:31]
	v_mfma_f32_32x32x16_bf16 v[16:31], v[112:115], v[180:183], v[16:31]
	s_mov_b32 m0, s6
	s_nop 0
	global_load_lds_dwordx4 v[184:185], off
	s_add_i32 m0, s6, 0x2000
	s_lshl_b32 s6, s13, 14
	s_addk_i32 s6, 0xc000
	s_cmp_gt_i32 s13, 0
	s_cselect_b32 s6, s6, 0xc000
	s_add_i32 s6, s63, s6
	global_load_lds_dwordx4 v[188:189], off
	s_mov_b32 m0, s6
	v_lshl_add_u64 v[184:185], v[184:185], 0, s[74:75]
	global_load_lds_dwordx4 v[186:187], off
	s_add_i32 m0, s6, 0x2000
	v_lshl_add_u64 v[188:189], v[188:189], 0, s[74:75]
	global_load_lds_dwordx4 v[190:191], off
	v_lshl_add_u64 v[186:187], v[186:187], 0, s[74:75]
	v_lshl_add_u64 v[190:191], v[190:191], 0, s[74:75]
	s_cbranch_vccnz .LBB0_406
	s_branch .Lmy_fta_1

.LBB0_442:
	s_add_i32 s14, s81, s13
	s_waitcnt vmcnt(5) lgkmcnt(0)
	s_barrier
	s_branch .Lmy_r2b_0

.Lmy_ftb_0:
	s_cmpk_gt_u32 s17, 0xfc
	s_mov_b64 s[14:15], -1
	s_cbranch_scc1 .LBB0_475
	s_andn2_b64 vcc, exec, s[14:15]
	s_cbranch_vccnz .LBB0_448

.LBB0_454:
	s_add_i32 s12, s81, s18
	s_waitcnt vmcnt(5) lgkmcnt(0)
	s_barrier
	s_branch .Lmy_r2b_1

.Lmy_ftb_1:
	s_cmpk_gt_u32 s17, 0xfb
	s_mov_b64 s[12:13], -1
	s_cbranch_scc1 .LBB0_481
	s_andn2_b64 vcc, exec, s[12:13]
	s_cbranch_vccnz .LBB0_459

; #define SBAR() __builtin_amdgcn_sched_barrier(0)
; template <int D0> __device__ __forceinline__ void pv_one(f32x16& od, int vb, bf16x8 pa0, bf16x8 pa1, bf16x8 pa2, bf16x8 pa3) {
;     const s16x4 l0 = tr_read<v_rd_off(D0, 0, 0)>(vb), h0 = tr_read<v_rd_off(D0, 0, 1)>(vb), l1 = tr_read<v_rd_off(D0, 1, 0)>(vb), h1 = tr_read<v_rd_off(D0, 1, 1)>(vb);
;     const s16x4 l2 = tr_read<v_rd_off(D0, 2, 0)>(vb), h2 = tr_read<v_rd_off(D0, 2, 1)>(vb), l3 = tr_read<v_rd_off(D0, 3, 0)>(vb), h3 = tr_read<v_rd_off(D0, 3, 1)>(vb);
;     asm volatile("s_waitcnt lgkmcnt(0)" ::: "memory"); SBAR();
;     ...
;     od = __builtin_amdgcn_mfma_f32_32x32x16_bf16(pa0, PK(l0, h0), od, 0, 0, 0);
;     od = __builtin_amdgcn_mfma_f32_32x32x16_bf16(pa1, PK(l1, h1), od, 0, 0, 0);
;     od = __builtin_amdgcn_mfma_f32_32x32x16_bf16(pa2, PK(l2, h2), od, 0, 0, 0);
;     od = __builtin_amdgcn_mfma_f32_32x32x16_bf16(pa3, PK(l3, h3), od, 0, 0, 0);
;     ...
; }
; template <bool RSM> __device__ __forceinline__ void pv_d0(f32x16* o, f32x16& lacc, int vb, bf16x8 pa0, bf16x8 pa1, bf16x8 pa2, bf16x8 pa3) {
;     if (RSM) {
;         const bf16x8 ones = {0x3F80, 0x3F80, 0x3F80, 0x3F80, 0x3F80, 0x3F80, 0x3F80, 0x3F80};
;         lacc = __builtin_amdgcn_mfma_f32_32x32x16_bf16(pa0, ones, lacc, 0, 0, 0);
;         lacc = __builtin_amdgcn_mfma_f32_32x32x16_bf16(pa1, ones, lacc, 0, 0, 0);
;         lacc = __builtin_amdgcn_mfma_f32_32x32x16_bf16(pa2, ones, lacc, 0, 0, 0);
;         lacc = __builtin_amdgcn_mfma_f32_32x32x16_bf16(pa3, ones, lacc, 0, 0, 0); }
;     pv_one<0>(o[0], vb, pa0, pa1, pa2, pa3); pv_one<1>(o[1], vb, pa0, pa1, pa2, pa3); pv_one<2>(o[2], vb, pa0, pa1, pa2, pa3); pv_one<3>(o[3], vb, pa0, pa1, pa2, pa3);
.Lmy_r2b_0:
	s_lshl_b32 s18, s12, 14
	v_add_u32_e32 v197, s18, v177
	ds_read_b64_tr_b16 v[172:173], v197 offset:0
	ds_read_b64_tr_b16 v[174:175], v197 offset:0x800
	ds_read_b64_tr_b16 v[198:199], v197 offset:0x1000
	ds_read_b64_tr_b16 v[200:201], v197 offset:0x1800
	ds_read_b64_tr_b16 v[208:209], v197 offset:0x2000
	ds_read_b64_tr_b16 v[210:211], v197 offset:0x2800
	ds_read_b64_tr_b16 v[212:213], v197 offset:0x3000
	ds_read_b64_tr_b16 v[214:215], v197 offset:0x3800
	s_waitcnt lgkmcnt(0)
	s_nop 0
	v_mfma_f32_32x32x16_bf16 v[50:65], v[146:149], v[172:175], v[50:65]
	ds_read_b64_tr_b16 v[172:173], v197 offset:0x200
	ds_read_b64_tr_b16 v[174:175], v197 offset:0xa00
	v_mfma_f32_32x32x16_bf16 v[50:65], v[150:153], v[198:201], v[50:65]
	ds_read_b64_tr_b16 v[198:199], v197 offset:0x1200
	ds_read_b64_tr_b16 v[200:201], v197 offset:0x1a00
	v_mfma_f32_32x32x16_bf16 v[50:65], v[154:157], v[208:211], v[50:65]
	ds_read_b64_tr_b16 v[208:209], v197 offset:0x2200
	ds_read_b64_tr_b16 v[210:211], v197 offset:0x2a00
	v_mfma_f32_32x32x16_bf16 v[50:65], v[158:161], v[212:215], v[50:65]
	ds_read_b64_tr_b16 v[212:213], v197 offset:0x3200
	ds_read_b64_tr_b16 v[214:215], v197 offset:0x3a00
	s_waitcnt lgkmcnt(0)
	v_mfma_f32_32x32x16_bf16 v[34:49], v[146:149], v[172:175], v[34:49]
	ds_read_b64_tr_b16 v[172:173], v197 offset:0x400
	ds_read_b64_tr_b16 v[174:175], v197 offset:0xc00
	v_mfma_f32_32x32x16_bf16 v[34:49], v[150:153], v[198:201], v[34:49]
	ds_read_b64_tr_b16 v[198:199], v197 offset:0x1400
	ds_read_b64_tr_b16 v[200:201], v197 offset:0x1c00
	v_mfma_f32_32x32x16_bf16 v[34:49], v[154:157], v[208:211], v[34:49]
	ds_read_b64_tr_b16 v[208:209], v197 offset:0x2400
	ds_read_b64_tr_b16 v[210:211], v197 offset:0x2c00
	v_mfma_f32_32x32x16_bf16 v[34:49], v[158:161], v[212:215], v[34:49]
	ds_read_b64_tr_b16 v[212:213], v197 offset:0x3400
	ds_read_b64_tr_b16 v[214:215], v197 offset:0x3c00
	s_waitcnt lgkmcnt(0)
	v_mfma_f32_32x32x16_bf16 v[18:33], v[146:149], v[172:175], v[18:33]
	ds_read_b64_tr_b16 v[172:173], v197 offset:0x600
	ds_read_b64_tr_b16 v[174:175], v197 offset:0xe00
	v_mfma_f32_32x32x16_bf16 v[18:33], v[150:153], v[198:201], v[18:33]
	ds_read_b64_tr_b16 v[198:199], v197 offset:0x1600
	ds_read_b64_tr_b16 v[200:201], v197 offset:0x1e00
	v_mfma_f32_32x32x16_bf16 v[18:33], v[154:157], v[208:211], v[18:33]
	ds_read_b64_tr_b16 v[208:209], v197 offset:0x2600
	ds_read_b64_tr_b16 v[210:211], v197 offset:0x2e00
	v_mfma_f32_32x32x16_bf16 v[18:33], v[158:161], v[212:215], v[18:33]
	ds_read_b64_tr_b16 v[212:213], v197 offset:0x3600
	ds_read_b64_tr_b16 v[214:215], v197 offset:0x3e00
	s_waitcnt lgkmcnt(0)
	v_mfma_f32_32x32x16_bf16 v[2:17], v[146:149], v[172:175], v[2:17]
	s_and_b64 vcc, exec, s[0:1]
	v_mfma_f32_32x32x16_bf16 v[2:17], v[150:153], v[198:201], v[2:17]
	v_mfma_f32_32x32x16_bf16 v[2:17], v[154:157], v[208:211], v[2:17]
	v_mfma_f32_32x32x16_bf16 v[2:17], v[158:161], v[212:215], v[2:17]
	s_mov_b32 m0, s14
	v_lshl_add_u64 v[172:173], v[170:171], 0, s[94:95]
	global_load_lds_dwordx4 v[162:163], off
	s_add_i32 m0, s14, 0x2000
	v_lshl_add_u64 v[162:163], v[162:163], 0, s[94:95]
	global_load_lds_dwordx4 v[164:165], off
	s_add_i32 m0, s14, 0x4000
	s_lshl_b32 s14, s12, 14
	s_addk_i32 s14, 0xc000
	s_cmp_gt_i32 s12, 0
	s_cselect_b32 s14, s14, 0xc000
	s_add_i32 s14, s63, s14
	global_load_lds_dwordx4 v[166:167], off
	s_mov_b32 m0, s14
	v_lshl_add_u64 v[164:165], v[164:165], 0, s[94:95]
	global_load_lds_dwordx4 v[170:171], off
	s_add_i32 m0, s14, 0x2000
	v_lshl_add_u64 v[166:167], v[166:167], 0, s[74:75]
	global_load_lds_dwordx4 v[168:169], off
	v_lshl_add_u64 v[174:175], v[168:169], 0, s[94:95]
	v_mov_b64_e32 v[168:169], v[174:175]
	v_mov_b64_e32 v[170:171], v[172:173]
	s_cbranch_vccnz .LBB0_449
	s_branch .Lmy_ftb_0
; #define SBAR() __builtin_amdgcn_sched_barrier(0)
; template <int D0> __device__ __forceinline__ void pv_one(f32x16& od, int vb, bf16x8 pa0, bf16x8 pa1, bf16x8 pa2, bf16x8 pa3) {
;     const s16x4 l0 = tr_read<v_rd_off(D0, 0, 0)>(vb), h0 = tr_read<v_rd_off(D0, 0, 1)>(vb), l1 = tr_read<v_rd_off(D0, 1, 0)>(vb), h1 = tr_read<v_rd_off(D0, 1, 1)>(vb);
;     const s16x4 l2 = tr_read<v_rd_off(D0, 2, 0)>(vb), h2 = tr_read<v_rd_off(D0, 2, 1)>(vb), l3 = tr_read<v_rd_off(D0, 3, 0)>(vb), h3 = tr_read<v_rd_off(D0, 3, 1)>(vb);
;     asm volatile("s_waitcnt lgkmcnt(0)" ::: "memory"); SBAR();
;     ...
;     od = __builtin_amdgcn_mfma_f32_32x32x16_bf16(pa0, PK(l0, h0), od, 0, 0, 0);
;     od = __builtin_amdgcn_mfma_f32_32x32x16_bf16(pa1, PK(l1, h1), od, 0, 0, 0);
;     od = __builtin_amdgcn_mfma_f32_32x32x16_bf16(pa2, PK(l2, h2), od, 0, 0, 0);
;     od = __builtin_amdgcn_mfma_f32_32x32x16_bf16(pa3, PK(l3, h3), od, 0, 0, 0);
;     ...
; }
; template <bool RSM> __device__ __forceinline__ void pv_d0(f32x16* o, f32x16& lacc, int vb, bf16x8 pa0, bf16x8 pa1, bf16x8 pa2, bf16x8 pa3) {
;     if (RSM) {
;         const bf16x8 ones = {0x3F80, 0x3F80, 0x3F80, 0x3F80, 0x3F80, 0x3F80, 0x3F80, 0x3F80};
;         lacc = __builtin_amdgcn_mfma_f32_32x32x16_bf16(pa0, ones, lacc, 0, 0, 0);
;         lacc = __builtin_amdgcn_mfma_f32_32x32x16_bf16(pa1, ones, lacc, 0, 0, 0);
;         lacc = __builtin_amdgcn_mfma_f32_32x32x16_bf16(pa2, ones, lacc, 0, 0, 0);
;         lacc = __builtin_amdgcn_mfma_f32_32x32x16_bf16(pa3, ones, lacc, 0, 0, 0); }
;     pv_one<0>(o[0], vb, pa0, pa1, pa2, pa3); pv_one<1>(o[1], vb, pa0, pa1, pa2, pa3); pv_one<2>(o[2], vb, pa0, pa1, pa2, pa3); pv_one<3>(o[3], vb, pa0, pa1, pa2, pa3);
.Lmy_r2b_1:
	s_lshl_b32 s19, s15, 14
	v_add_u32_e32 v175, s19, v177
	ds_read_b64_tr_b16 v[198:199], v175 offset:0
	ds_read_b64_tr_b16 v[200:201], v175 offset:0x800
	ds_read_b64_tr_b16 v[208:209], v175 offset:0x1000
	ds_read_b64_tr_b16 v[210:211], v175 offset:0x1800
	ds_read_b64_tr_b16 v[212:213], v175 offset:0x2000
	ds_read_b64_tr_b16 v[214:215], v175 offset:0x2800
	ds_read_b64_tr_b16 v[226:227], v175 offset:0x3000
	ds_read_b64_tr_b16 v[228:229], v175 offset:0x3800
	s_waitcnt lgkmcnt(0)
	s_nop 0
	v_mfma_f32_32x32x16_bf16 v[50:65], v[146:149], v[198:201], v[50:65]
	ds_read_b64_tr_b16 v[198:199], v175 offset:0x200
	ds_read_b64_tr_b16 v[200:201], v175 offset:0xa00
	v_mfma_f32_32x32x16_bf16 v[50:65], v[150:153], v[208:211], v[50:65]
	ds_read_b64_tr_b16 v[208:209], v175 offset:0x1200
	ds_read_b64_tr_b16 v[210:211], v175 offset:0x1a00
	v_mfma_f32_32x32x16_bf16 v[50:65], v[154:157], v[212:215], v[50:65]
	ds_read_b64_tr_b16 v[212:213], v175 offset:0x2200
	ds_read_b64_tr_b16 v[214:215], v175 offset:0x2a00
	v_mfma_f32_32x32x16_bf16 v[50:65], v[158:161], v[226:229], v[50:65]
	ds_read_b64_tr_b16 v[226:227], v175 offset:0x3200
	ds_read_b64_tr_b16 v[228:229], v175 offset:0x3a00
	s_waitcnt lgkmcnt(0)
	v_mfma_f32_32x32x16_bf16 v[34:49], v[146:149], v[198:201], v[34:49]
	ds_read_b64_tr_b16 v[198:199], v175 offset:0x400
	ds_read_b64_tr_b16 v[200:201], v175 offset:0xc00
	v_mfma_f32_32x32x16_bf16 v[34:49], v[150:153], v[208:211], v[34:49]
	ds_read_b64_tr_b16 v[208:209], v175 offset:0x1400
	ds_read_b64_tr_b16 v[210:211], v175 offset:0x1c00
	v_mfma_f32_32x32x16_bf16 v[34:49], v[154:157], v[212:215], v[34:49]
	ds_read_b64_tr_b16 v[212:213], v175 offset:0x2400
	ds_read_b64_tr_b16 v[214:215], v175 offset:0x2c00
	v_mfma_f32_32x32x16_bf16 v[34:49], v[158:161], v[226:229], v[34:49]
	ds_read_b64_tr_b16 v[226:227], v175 offset:0x3400
	ds_read_b64_tr_b16 v[228:229], v175 offset:0x3c00
	s_waitcnt lgkmcnt(0)
	v_mfma_f32_32x32x16_bf16 v[18:33], v[146:149], v[198:201], v[18:33]
	ds_read_b64_tr_b16 v[198:199], v175 offset:0x600
	ds_read_b64_tr_b16 v[200:201], v175 offset:0xe00
	v_mfma_f32_32x32x16_bf16 v[18:33], v[150:153], v[208:211], v[18:33]
	ds_read_b64_tr_b16 v[208:209], v175 offset:0x1600
	ds_read_b64_tr_b16 v[210:211], v175 offset:0x1e00
	v_mfma_f32_32x32x16_bf16 v[18:33], v[154:157], v[212:215], v[18:33]
	ds_read_b64_tr_b16 v[212:213], v175 offset:0x2600
	ds_read_b64_tr_b16 v[214:215], v175 offset:0x2e00
	v_mfma_f32_32x32x16_bf16 v[18:33], v[158:161], v[226:229], v[18:33]
	ds_read_b64_tr_b16 v[226:227], v175 offset:0x3600
	ds_read_b64_tr_b16 v[228:229], v175 offset:0x3e00
	s_waitcnt lgkmcnt(0)
	v_mfma_f32_32x32x16_bf16 v[2:17], v[146:149], v[198:201], v[2:17]
	s_and_b64 vcc, exec, s[0:1]
	v_mfma_f32_32x32x16_bf16 v[2:17], v[150:153], v[208:211], v[2:17]
	v_mfma_f32_32x32x16_bf16 v[2:17], v[154:157], v[212:215], v[2:17]
	v_mfma_f32_32x32x16_bf16 v[2:17], v[158:161], v[226:229], v[2:17]
	s_mov_b32 m0, s12
	s_nop 0
	global_load_lds_dwordx4 v[162:163], off
	s_add_i32 m0, s12, 0x2000
	v_lshl_add_u64 v[162:163], v[162:163], 0, s[94:95]
	global_load_lds_dwordx4 v[164:165], off
	s_add_i32 m0, s12, 0x4000
	s_lshl_b32 s12, s15, 14
	s_addk_i32 s12, 0xc000
	s_cmp_gt_i32 s15, 0
	s_cselect_b32 s12, s12, 0xc000
	s_add_i32 s12, s63, s12
	global_load_lds_dwordx4 v[166:167], off
	s_mov_b32 m0, s12
	v_lshl_add_u64 v[164:165], v[164:165], 0, s[94:95]
	global_load_lds_dwordx4 v[170:171], off
	s_add_i32 m0, s12, 0x2000
	v_lshl_add_u64 v[166:167], v[166:167], 0, s[74:75]
	global_load_lds_dwordx4 v[168:169], off
	v_lshl_add_u64 v[170:171], v[170:171], 0, s[94:95]
	v_lshl_add_u64 v[168:169], v[168:169], 0, s[94:95]
	s_cbranch_vccnz .LBB0_459
	s_branch .Lmy_ftb_1
